# stack on v40: row_pass register prefetch + lng/lnb reload removal + p3_row DPP/permlane-swap wave reductions
# baseline (speedup 1.0000x reference)
; DI unsigned cvtpk(float lo, float hi) { f32x2 v = {lo, hi}; bf16x2_t b = __builtin_convertvector(v, bf16x2_t); return __builtin_bit_cast(unsigned, b); }
; DI float bf2f(unsigned short b) { return __uint_as_float(((unsigned)b) << 16); }
; DI float bflo(unsigned w) { return __uint_as_float(w << 16); }
; DI float bfhi(unsigned w) { return __uint_as_float(w & 0xffff0000u); }
; DI void p3_row(const Args& a, int m, int lane) {
;     ...
;     const u32x2 qw = *(const u32x2*)(U + 512 + 4 * lane), kw = *(const u32x2*)(U + 768 + 4 * lane);
;     float q[4] = {bflo(qw.x), bfhi(qw.x), bflo(qw.y), bfhi(qw.y)}, k[4] = {bflo(kw.x), bfhi(kw.x), bflo(kw.y), bfhi(kw.y)};
;     const float qs = wave_sum(q[0] * q[0] + q[1] * q[1] + q[2] * q[2] + q[3] * q[3]), ks = wave_sum(k[0] * k[0] + k[1] * k[1] + k[2] * k[2] + k[3] * k[3]);
;     const float qr = 1.0f / sqrtf(qs * (1.0f / 256.0f) + RMS_EPS), kr_ = 1.0f / sqrtf(ks * (1.0f / 256.0f) + RMS_EPS);
;     const f32x4 qg = *(const f32x4*)(a.in[I0_QN] + 4 * lane), kg = *(const f32x4*)(a.in[I0_KVN] + 4 * lane);
;     u32x2 w; w.x = cvtpk(q[0] * qr * qg[0], q[1] * qr * qg[1]); w.y = cvtpk(q[2] * qr * qg[2], q[3] * qr * qg[3]);
;     *(u32x2*)((bf16_t*)(ws + WS_CQN) + (size_t)m * 256 + 4 * lane) = w;
;     w.x = cvtpk(k[0] * kr_ * kg[0], k[1] * kr_ * kg[1]); w.y = cvtpk(k[2] * kr_ * kg[2], k[3] * kr_ * kg[3]);
;     *(u32x2*)((bf16_t*)(ws + WS_CKVN) + (size_t)m * 256 + 4 * lane) = w;
;     const int d = lane & 31, t = d >> 3, f = d & 7; const float val = bf2f(U[1024 + d]); const float par = __shfl_xor(val, 8);
;     const int j = m % TPB, tt = j - CTX; float outv = val;
;     if (tt >= 0) { const int pos = (t < 2) ? (tt >> 6) : (tt & 63); const f32x2 cs = ((const f32x2*)(ws + WS_TAB8))[pos * 8 + f];
;         outv = (t & 1) ? (par * cs[1] + val * cs[0]) : (val * cs[0] - par * cs[1]); }
;     if (lane < 32) ((bf16_t*)(ws + WS_KR))[(size_t)m * 32 + 16 * (t & 1) + 8 * (t >> 1) + f] = (bf16_t)(cvtpk(outv, 0.f) & 0xffffu);
.LBB0_343:
	s_waitcnt lgkmcnt(0)
	v_lshl_add_u64 v[12:13], s[16:17], 0, v[8:9]
	v_add_co_u32_e32 v12, vcc, 0xfa00000, v12
	v_lshl_add_u64 v[36:37], s[16:17], 0, v[6:7]
	s_nop 0
	v_addc_co_u32_e32 v13, vcc, 0, v13, vcc
	global_load_dwordx2 v[24:25], v[12:13], off offset:1024
	global_load_dwordx2 v[26:27], v[12:13], off offset:1536
	s_mov_b32 s4, 0x14c80000
	s_mov_b32 s5, 0x15d00000
	s_waitcnt vmcnt(1)
	v_lshlrev_b32_e32 v14, 16, v24
	v_and_b32_e32 v15, 0xffff0000, v24
	s_waitcnt vmcnt(0)
	v_lshlrev_b32_e32 v34, 16, v26
	v_and_b32_e32 v35, 0xffff0000, v26
	v_lshlrev_b32_e32 v12, 16, v25
	v_and_b32_e32 v13, 0xffff0000, v25
	v_lshlrev_b32_e32 v32, 16, v27
	v_and_b32_e32 v33, 0xffff0000, v27
	v_pk_mul_f32 v[26:27], v[14:15], v[14:15]
	v_pk_mul_f32 v[30:31], v[34:35], v[34:35]
	v_pk_mul_f32 v[24:25], v[12:13], v[12:13]
	v_pk_mul_f32 v[28:29], v[32:33], v[32:33]
	v_add_f32_e32 v23, v26, v27
	v_add_f32_e32 v26, v30, v31
	v_add_f32_e32 v23, v24, v23
	v_add_f32_e32 v24, v28, v26
	v_add_f32_e32 v23, v25, v23
	v_add_f32_e32 v24, v29, v24
	s_nop 1
	v_add_f32_dpp v39, v23, v23 quad_perm:[1,0,3,2] row_mask:0xf bank_mask:0xf
	v_add_f32_dpp v41, v24, v24 quad_perm:[1,0,3,2] row_mask:0xf bank_mask:0xf
	global_load_dwordx4 v[24:27], v[0:1], off
	global_load_dwordx4 v[28:31], v[2:3], off
	v_add_f32_dpp v43, v39, v39 quad_perm:[2,3,0,1] row_mask:0xf bank_mask:0xf
	v_add_f32_dpp v44, v41, v41 quad_perm:[2,3,0,1] row_mask:0xf bank_mask:0xf
	s_nop 0
	v_add_f32_dpp v39, v43, v43 row_half_mirror row_mask:0xf bank_mask:0xf
	v_add_f32_dpp v41, v44, v44 row_half_mirror row_mask:0xf bank_mask:0xf
	s_nop 0
	v_add_f32_dpp v43, v39, v39 row_mirror row_mask:0xf bank_mask:0xf
	v_add_f32_dpp v44, v41, v41 row_mirror row_mask:0xf bank_mask:0xf
	v_mov_b32_e32 v39, v43
	v_mov_b32_e32 v41, v44
	s_nop 1
	v_permlane16_swap_b32_e32 v39, v43
	v_permlane16_swap_b32_e32 v41, v44
	v_add_f32_e32 v43, v39, v43
	v_add_f32_e32 v44, v41, v44
	v_mov_b32_e32 v39, v43
	v_mov_b32_e32 v41, v44
	s_nop 1
	v_permlane32_swap_b32_e32 v39, v43
	v_permlane32_swap_b32_e32 v41, v44
	v_add_f32_e32 v23, v39, v43
	v_add_f32_e32 v42, v41, v44
	v_lshl_add_u64 v[38:39], s[16:17], 0, v[10:11]
	v_add_co_u32_e32 v40, vcc, s4, v36
	v_add_co_u32_e64 v36, s[46:47], s5, v36
	s_nop 0
	v_addc_co_u32_e32 v41, vcc, 0, v37, vcc
	v_fmamk_f32 v23, v23, 0x3b800000, v172
	v_fmamk_f32 v42, v42, 0x3b800000, v172
	v_mul_f32_e32 v43, 0x4f800000, v23
	v_cmp_gt_f32_e32 vcc, s80, v23
	v_mul_f32_e32 v44, 0x4f800000, v42
	v_cmp_gt_f32_e64 s[44:45], s80, v42
	v_cndmask_b32_e32 v23, v23, v43, vcc
	v_sqrt_f32_e32 v43, v23
	v_cndmask_b32_e64 v42, v42, v44, s[44:45]
	v_sqrt_f32_e32 v44, v42
	v_addc_co_u32_e64 v37, s[46:47], 0, v37, s[46:47]
	v_add_u32_e32 v45, -1, v43
	v_add_u32_e32 v47, -1, v44
	v_fma_f32 v49, -v45, v43, v23
	v_add_u32_e32 v46, 1, v43
	v_fma_f32 v51, -v47, v44, v42
	v_cmp_ge_f32_e64 s[46:47], 0, v49
	v_add_u32_e32 v48, 1, v44
	v_fma_f32 v50, -v46, v43, v23
	v_cndmask_b32_e64 v43, v43, v45, s[46:47]
	v_cmp_ge_f32_e64 s[46:47], 0, v51
	v_fma_f32 v52, -v48, v44, v42
	s_nop 0
	v_cndmask_b32_e64 v44, v44, v47, s[46:47]
	v_cmp_lt_f32_e64 s[46:47], 0, v50
	s_nop 1
	v_cndmask_b32_e64 v43, v43, v46, s[46:47]
	v_cmp_lt_f32_e64 s[46:47], 0, v52
	v_mul_f32_e32 v45, 0x37800000, v43
	v_cndmask_b32_e32 v43, v43, v45, vcc
	v_cndmask_b32_e64 v44, v44, v48, s[46:47]
	v_mul_f32_e32 v46, 0x37800000, v44
	v_cmp_class_f32_e32 vcc, v23, v173
	v_cndmask_b32_e64 v44, v44, v46, s[44:45]
	s_nop 0
	v_cndmask_b32_e32 v23, v43, v23, vcc
	v_cmp_class_f32_e32 vcc, v42, v173
	s_nop 1
	v_cndmask_b32_e32 v43, v44, v42, vcc
	v_div_scale_f32 v42, s[4:5], v23, v23, 1.0
	v_div_scale_f32 v45, s[4:5], v43, v43, 1.0
	v_rcp_f32_e32 v46, v42
	v_rcp_f32_e32 v47, v45
	v_div_scale_f32 v44, vcc, 1.0, v23, 1.0
	v_fma_f32 v49, -v42, v46, 1.0
	v_fma_f32 v50, -v45, v47, 1.0
	v_fmac_f32_e32 v46, v49, v46
	v_div_scale_f32 v48, s[44:45], 1.0, v43, 1.0
	v_fmac_f32_e32 v47, v50, v47
	v_mul_f32_e32 v49, v44, v46
	v_mul_f32_e32 v50, v48, v47
	v_fma_f32 v51, -v42, v49, v44
	v_fma_f32 v52, -v45, v50, v48
	v_fmac_f32_e32 v49, v51, v46
	v_fmac_f32_e32 v50, v52, v47
	v_fma_f32 v42, -v42, v49, v44
	v_fma_f32 v44, -v45, v50, v48
	v_div_fmas_f32 v42, v42, v46, v49
	s_mov_b64 vcc, s[44:45]
	v_div_fixup_f32 v42, v42, v23, 1.0
	v_div_fmas_f32 v23, v44, v47, v50
	v_pk_mul_f32 v[14:15], v[42:43], v[14:15] op_sel_hi:[0,1]
	v_pk_mul_f32 v[12:13], v[42:43], v[12:13] op_sel_hi:[0,1]
	v_div_fixup_f32 v42, v23, v43, 1.0
	s_waitcnt vmcnt(1)
	v_pk_mul_f32 v[14:15], v[24:25], v[14:15]
	v_pk_mul_f32 v[12:13], v[26:27], v[12:13]
	v_pk_mul_f32 v[24:25], v[42:43], v[34:35] op_sel_hi:[0,1]
	v_pk_mul_f32 v[26:27], v[42:43], v[32:33] op_sel_hi:[0,1]
	v_cvt_pk_bf16_f32 v14, v14, v15
	v_cvt_pk_bf16_f32 v15, v12, v13
	s_waitcnt vmcnt(0)
	v_pk_mul_f32 v[12:13], v[28:29], v[24:25]
	v_pk_mul_f32 v[24:25], v[30:31], v[26:27]
	v_cvt_pk_bf16_f32 v12, v12, v13
	v_cvt_pk_bf16_f32 v13, v24, v25
	global_store_dwordx2 v[40:41], v[14:15], off
	global_store_dwordx2 v[36:37], v[12:13], off
	global_load_ushort v12, v[38:39], off
	s_mul_hi_i32 s4, s76, 0x3e0f83e1
	s_lshr_b32 s5, s4, 31
	s_ashr_i32 s4, s4, 11
	s_add_i32 s4, s4, s5
	s_mulk_i32 s4, 0x2100
	s_sub_i32 s4, s76, s4
	s_cmpk_lt_i32 s4, 0x100
	s_waitcnt vmcnt(0)
	v_lshlrev_b32_e32 v12, 16, v12
	ds_bpermute_b32 v13, v19, v12
	s_cbranch_scc1 .LBB0_345
	s_add_i32 s5, s4, 0xffffff00
	s_lshr_b32 s5, s5, 6
	s_and_b32 s4, s4, 63
	v_mov_b32_e32 v14, s4
	v_mov_b32_e32 v15, s5
	v_cndmask_b32_e64 v14, v14, v15, s[0:1]
	v_lshlrev_b32_e32 v15, 3, v22
	v_readlane_b32 s4, v245, 47
	v_lshl_or_b32 v14, v14, 6, v15
	v_readlane_b32 s5, v245, 48
	s_nop 4
	global_load_dwordx2 v[14:15], v14, s[4:5]
	s_waitcnt vmcnt(0) lgkmcnt(0)
	v_mul_f32_e32 v13, v15, v13
	v_cndmask_b32_e64 v13, v13, -v13, s[40:41]
	v_fmac_f32_e32 v13, v14, v12
	v_mov_b32_e32 v12, v13
